# baseline (speedup 1.0000x reference)
; #define SBAR() __builtin_amdgcn_sched_barrier(0)
; #define SWAIT() asm volatile("s_waitcnt vmcnt(4)" ::: "memory")
; template <int D0> DEVFI void pv_one(f32x16& od, int vb, bf16x8 pa0, bf16x8 pa1, bf16x8 pa2, bf16x8 pa3) {
;   const s16x4 l0 = tr_read<v_rd_off(D0, 0, 0)>(vb), h0 = tr_read<v_rd_off(D0, 0, 1)>(vb), l1 = tr_read<v_rd_off(D0, 1, 0)>(vb), h1 = tr_read<v_rd_off(D0, 1, 1)>(vb);
;   const s16x4 l2 = tr_read<v_rd_off(D0, 2, 0)>(vb), h2 = tr_read<v_rd_off(D0, 2, 1)>(vb), l3 = tr_read<v_rd_off(D0, 3, 0)>(vb), h3 = tr_read<v_rd_off(D0, 3, 1)>(vb);
;   asm volatile("s_waitcnt lgkmcnt(0)" ::: "memory"); SBAR();
;     ...
;   od = __builtin_amdgcn_mfma_f32_32x32x16_bf16(pa0, PKV(l0, h0), od, 0, 0, 0);
;   od = __builtin_amdgcn_mfma_f32_32x32x16_bf16(pa1, PKV(l1, h1), od, 0, 0, 0);
;   od = __builtin_amdgcn_mfma_f32_32x32x16_bf16(pa2, PKV(l2, h2), od, 0, 0, 0);
;   od = __builtin_amdgcn_mfma_f32_32x32x16_bf16(pa3, PKV(l3, h3), od, 0, 0, 0);
;     ...
; }
; DEVFI void pv_d0(f32x16* o, int vb, bf16x8 pa0, bf16x8 pa1, bf16x8 pa2, bf16x8 pa3) {
;   pv_one<0>(o[0], vb, pa0, pa1, pa2, pa3); pv_one<1>(o[1], vb, pa0, pa1, pa2, pa3); pv_one<2>(o[2], vb, pa0, pa1, pa2, pa3); pv_one<3>(o[3], vb, pa0, pa1, pa2, pa3);
; template <int LDQ, int LDK, int LDO>
; DEVFI void attn_dense_body(const bfraw* __restrict__ Qb, const bfraw* __restrict__ Kh, const bfraw* __restrict__ Vh,
;                            bfraw* __restrict__ Ob, int seq, char* lds, const int wv) {
;     ...
;   f32x16 pA0, pA1, pB0, pB1; float mnA, mnB, alA, alB; bf16x8 pa0, pa1, pa2, pa3; const int NT = seq / AKVBLK;
;   constexpr int SE = 0, SO = 1;
;   SLOAD(SE, 0); asm volatile("s_waitcnt vmcnt(0)" ::: "memory"); SWRITE(0, SE); __syncthreads();
;   qkt(pA0, pA1, K_lds, qr, r32, hi); partialSM(pA0, pA1, m_reg, mnA, alA);
;   SLOAD(SO, AKVBLK); if (2 < NT) SLOAD(SE, 2 * AKVBLK);
;   SWAIT(); SWRITE(1, SO); __syncthreads();
;   for (int j = 1; j + 1 < NT; j += 2) {
;     SBAR(); qkt(pB0, pB1, K_lds + SHM_K, qr, r32, hi);
;     finishSM(pA0, pA1, alA, l_reg, pa0, pa1, pa2, pa3); SBAR();
;     SLOAD(SO, (j + 2) * AKVBLK); SBAR();
;     pv_d0(o, vb0, pa0, pa1, pa2, pa3); partialSM(pB0, pB1, m_reg, mnB, alB);
;     __syncthreads(); SWAIT(); SWRITE(0, SE);
;     RESC(alB); __syncthreads();
.LBB0_2466:
	ds_read_b64_tr_b16 v[190:191], v198 offset:0
	ds_read_b64_tr_b16 v[192:193], v198 offset:0x800
	ds_read_b64_tr_b16 v[230:231], v198 offset:0x1000
	ds_read_b64_tr_b16 v[232:233], v198 offset:0x1800
	ds_read_b64_tr_b16 v[234:235], v198 offset:0x2000
	ds_read_b64_tr_b16 v[236:237], v198 offset:0x2800
	ds_read_b64_tr_b16 v[238:239], v198 offset:0x3000
	ds_read_b64_tr_b16 v[240:241], v198 offset:0x3800
	s_waitcnt lgkmcnt(0)
	s_nop 0
	v_mfma_f32_32x32x16_bf16 v[0:15], v[160:163], v[190:193], v[0:15]
	ds_read_b64_tr_b16 v[190:191], v198 offset:0x200
	ds_read_b64_tr_b16 v[192:193], v198 offset:0xa00
	v_mfma_f32_32x32x16_bf16 v[0:15], v[164:167], v[230:233], v[0:15]
	ds_read_b64_tr_b16 v[230:231], v198 offset:0x1200
	ds_read_b64_tr_b16 v[232:233], v198 offset:0x1a00
	v_mfma_f32_32x32x16_bf16 v[0:15], v[168:171], v[234:237], v[0:15]
	ds_read_b64_tr_b16 v[234:235], v198 offset:0x2200
	ds_read_b64_tr_b16 v[236:237], v198 offset:0x2a00
	v_mfma_f32_32x32x16_bf16 v[0:15], v[172:175], v[238:241], v[0:15]
	ds_read_b64_tr_b16 v[238:239], v198 offset:0x3200
	ds_read_b64_tr_b16 v[240:241], v198 offset:0x3a00
	s_waitcnt lgkmcnt(0)
	v_mfma_f32_32x32x16_bf16 v[48:63], v[160:163], v[190:193], v[48:63]
	ds_read_b64_tr_b16 v[190:191], v198 offset:0x400
	ds_read_b64_tr_b16 v[192:193], v198 offset:0xc00
	v_mfma_f32_32x32x16_bf16 v[48:63], v[164:167], v[230:233], v[48:63]
	ds_read_b64_tr_b16 v[230:231], v198 offset:0x1400
	ds_read_b64_tr_b16 v[232:233], v198 offset:0x1c00
	v_mfma_f32_32x32x16_bf16 v[48:63], v[168:171], v[234:237], v[48:63]
	ds_read_b64_tr_b16 v[234:235], v198 offset:0x2400
	ds_read_b64_tr_b16 v[236:237], v198 offset:0x2c00
	v_mfma_f32_32x32x16_bf16 v[48:63], v[172:175], v[238:241], v[48:63]
	ds_read_b64_tr_b16 v[238:239], v198 offset:0x3400
	ds_read_b64_tr_b16 v[240:241], v198 offset:0x3c00
	s_waitcnt lgkmcnt(0)
	v_mfma_f32_32x32x16_bf16 v[32:47], v[160:163], v[190:193], v[32:47]
	ds_read_b64_tr_b16 v[190:191], v198 offset:0x600
	ds_read_b64_tr_b16 v[192:193], v198 offset:0xe00
	v_mfma_f32_32x32x16_bf16 v[32:47], v[164:167], v[230:233], v[32:47]
	ds_read_b64_tr_b16 v[230:231], v198 offset:0x1600
	ds_read_b64_tr_b16 v[232:233], v198 offset:0x1e00
	v_mfma_f32_32x32x16_bf16 v[32:47], v[168:171], v[234:237], v[32:47]
	ds_read_b64_tr_b16 v[234:235], v198 offset:0x2600
	ds_read_b64_tr_b16 v[236:237], v198 offset:0x2e00
	v_mfma_f32_32x32x16_bf16 v[32:47], v[172:175], v[238:241], v[32:47]
	ds_read_b64_tr_b16 v[238:239], v198 offset:0x3600
	ds_read_b64_tr_b16 v[240:241], v198 offset:0x3e00
	s_waitcnt lgkmcnt(0)
	v_mfma_f32_32x32x16_bf16 v[16:31], v[160:163], v[190:193], v[16:31]
	v_max_f32_e32 v160, v81, v81
	v_max_f32_e32 v161, v80, v80
	v_max_f32_e32 v160, v161, v160
	v_max3_f32 v160, v160, v82, v83
	v_max3_f32 v160, v160, v84, v85
	v_max3_f32 v160, v160, v86, v87
	v_max3_f32 v160, v160, v88, v89
	v_max3_f32 v160, v160, v90, v91
	v_max3_f32 v160, v160, v92, v93
	v_mfma_f32_32x32x16_bf16 v[16:31], v[164:167], v[230:233], v[16:31]
	v_max3_f32 v160, v160, v94, v95
	v_max3_f32 v160, v160, v64, v65
	v_max3_f32 v160, v160, v66, v67
	v_max3_f32 v160, v160, v68, v69
	v_max3_f32 v160, v160, v70, v71
	v_max3_f32 v160, v160, v72, v73
	v_max3_f32 v160, v160, v74, v75
	v_max3_f32 v160, v160, v76, v77
	v_mfma_f32_32x32x16_bf16 v[16:31], v[168:171], v[234:237], v[16:31]
	v_max3_f32 v160, v160, v78, v79
	v_mov_b32_e32 v161, v160
	s_nop 1
	v_permlane32_swap_b32_e32 v160, v161
	v_max_f32_e32 v161, v161, v161
	v_max_f32_e32 v160, v160, v160
	v_max_f32_e32 v160, v160, v161
	v_sub_f32_e32 v161, v160, v226
	v_cmp_ge_f32_e32 vcc, s29, v161
	v_max_f32_e32 v161, v226, v226
	v_max_f32_e32 v161, v161, v160
	v_mfma_f32_32x32x16_bf16 v[16:31], v[172:175], v[238:241], v[16:31]
	v_sub_f32_e32 v160, v226, v161
	v_mul_f32_e32 v160, 0x3e0293ee, v160
	v_exp_f32_e32 v160, v160
	s_cmp_eq_u64 vcc, exec
	s_cselect_b64 s[8:9], -1, 0
	s_barrier
	s_waitcnt vmcnt(4)
	v_cndmask_b32_e64 v160, v160, 1.0, s[8:9]
	v_cmp_gt_f32_e32 vcc, 1.0, v160
	s_cmp_ge_u32 s80, s57
	s_cbranch_scc0 .Lattn_se_inflight
	s_waitcnt vmcnt(0)
.Lattn_se_inflight:
	ds_write_b128 v200, v[144:147] offset:16384
	ds_write_b128 v201, v[148:151] offset:16384
	ds_write_b128 v202, v[152:155] offset:49152
	ds_write_b128 v203, v[156:159] offset:49152
	s_cbranch_vccz .LBB0_2470
	s_and_saveexec_b64 s[2:3], s[6:7]
	ds_write_b32 v196, v160 offset:128
	s_or_b64 exec, exec, s[2:3]
	s_waitcnt lgkmcnt(0)
	v_add_u32_e32 v156, v185, v176
	ds_read_b128 v[144:147], v156 offset:224
	ds_read_b128 v[148:151], v156 offset:192
	ds_read_b128 v[152:155], v156 offset:160
	ds_read_b128 v[156:159], v156 offset:128
	s_waitcnt lgkmcnt(3)
	v_pk_mul_f32 v[12:13], v[12:13], v[144:145]
	s_waitcnt lgkmcnt(2)
	v_pk_mul_f32 v[8:9], v[8:9], v[148:149]
	s_waitcnt lgkmcnt(1)
	v_pk_mul_f32 v[4:5], v[4:5], v[152:153]
	v_pk_mul_f32 v[14:15], v[14:15], v[146:147]
	v_pk_mul_f32 v[10:11], v[10:11], v[150:151]
	v_pk_mul_f32 v[6:7], v[6:7], v[154:155]
	s_waitcnt lgkmcnt(0)
	v_pk_mul_f32 v[2:3], v[2:3], v[158:159]
	v_pk_mul_f32 v[0:1], v[0:1], v[156:157]
	v_pk_mul_f32 v[60:61], v[60:61], v[144:145]
	v_pk_mul_f32 v[56:57], v[56:57], v[148:149]
	v_pk_mul_f32 v[52:53], v[52:53], v[152:153]
	v_pk_mul_f32 v[62:63], v[62:63], v[146:147]
	v_pk_mul_f32 v[58:59], v[58:59], v[150:151]
	v_pk_mul_f32 v[54:55], v[54:55], v[154:155]
	v_pk_mul_f32 v[50:51], v[50:51], v[158:159]
	v_pk_mul_f32 v[48:49], v[48:49], v[156:157]
	v_pk_mul_f32 v[44:45], v[44:45], v[144:145]
	v_pk_mul_f32 v[40:41], v[40:41], v[148:149]
	v_pk_mul_f32 v[36:37], v[36:37], v[152:153]
	v_pk_mul_f32 v[46:47], v[46:47], v[146:147]
	v_pk_mul_f32 v[42:43], v[42:43], v[150:151]
	v_pk_mul_f32 v[38:39], v[38:39], v[154:155]
	v_pk_mul_f32 v[34:35], v[34:35], v[158:159]
	v_pk_mul_f32 v[32:33], v[32:33], v[156:157]
	v_pk_mul_f32 v[28:29], v[28:29], v[144:145]
	v_pk_mul_f32 v[24:25], v[24:25], v[148:149]
	v_pk_mul_f32 v[20:21], v[20:21], v[152:153]
	v_pk_mul_f32 v[30:31], v[30:31], v[146:147]
	v_pk_mul_f32 v[26:27], v[26:27], v[150:151]
	v_pk_mul_f32 v[22:23], v[22:23], v[154:155]
	v_pk_mul_f32 v[18:19], v[18:19], v[158:159]
	v_pk_mul_f32 v[16:17], v[16:17], v[156:157]
